# grid barriers: acquire L1 invalidate (buffer_inv sc1) issued at arrival behind the arrival atomic (vmcnt(1)) instead of after the release is observed
# speedup vs baseline: 1.0060x; 1.0060x over previous
.LBB0_124:
	s_or_b64 exec, exec, s[18:19]
	buffer_inv sc1
	v_cvt_f32_u32_e32 v4, v2
	s_waitcnt vmcnt(1)
	v_readfirstlane_b32 s3, v3
	v_sub_u32_e32 v3, 0, v2
	v_rcp_iflag_f32_e32 v4, v4
	v_add_u32_e32 v5, s3, v1
	v_mul_f32_e32 v4, 0x4f7ffffe, v4
	v_cvt_u32_f32_e32 v4, v4
	v_mul_lo_u32 v1, v3, v4
	v_mul_hi_u32 v1, v4, v1
	v_add_u32_e32 v1, v4, v1
	v_mul_hi_u32 v1, v5, v1
	v_mul_lo_u32 v3, v1, v2
	v_sub_u32_e32 v3, v5, v3
	v_add_u32_e32 v4, 1, v1
	v_cmp_ge_u32_e32 vcc, v3, v2
	s_nop 1
	v_cndmask_b32_e32 v1, v1, v4, vcc
	v_sub_u32_e32 v4, v3, v2
	v_cndmask_b32_e32 v3, v3, v4, vcc
	v_add_u32_e32 v4, 1, v1
	v_cmp_ge_u32_e32 vcc, v3, v2
	v_add_u32_e32 v3, 1, v5
	s_nop 0
	v_cndmask_b32_e32 v1, v1, v4, vcc
	v_mul_lo_u32 v4, v2, v1
	v_add_u32_e32 v2, v4, v2
	v_cmp_ne_u32_e32 vcc, v3, v2
	s_and_saveexec_b64 s[16:17], vcc
	s_xor_b64 s[16:17], exec, s[16:17]
	s_cbranch_execz .LBB0_138
	s_waitcnt lgkmcnt(0)
	v_mov_b32_e32 v0, 0x2000
	global_load_dword v0, v0, s[8:9] offset:1024 sc1
	s_add_u32 s22, s8, 0x2400
	s_addc_u32 s23, s9, 0
	s_waitcnt vmcnt(0)
	v_cmp_eq_u32_e32 vcc, v0, v1
	s_and_saveexec_b64 s[18:19], vcc
	s_cbranch_execz .LBB0_137
	s_add_u32 s20, s50, 0x80200
	s_addc_u32 s21, s51, 0
	s_mov_b32 s3, 1
	s_mov_b64 s[24:25], 0
	v_mov_b32_e32 v0, 0
	s_branch .LBB0_128

.LBB0_137:
	s_or_b64 exec, exec, s[18:19]
	s_waitcnt vmcnt(0)
	s_waitcnt vmcnt(0)

.LBB0_155:
	s_or_b64 exec, exec, s[16:17]
	s_mov_b64 s[16:17], exec
	v_mbcnt_lo_u32_b32 v0, s16, 0
	v_mbcnt_hi_u32_b32 v0, s17, v0
	v_cmp_eq_u32_e32 vcc, 0, v0
	s_waitcnt vmcnt(0)
	s_and_saveexec_b64 s[18:19], vcc
	s_cbranch_execz .LBB0_157
	s_bcnt1_i32_b64 s3, s[16:17]
	v_mov_b32_e32 v0, 0x2000
	v_mov_b32_e32 v1, s3
	global_atomic_add v0, v1, s[8:9] offset:1024

.LBB0_305:
	s_or_b64 exec, exec, s[16:17]
	buffer_inv sc1
	v_cvt_f32_u32_e32 v4, v2
	s_waitcnt vmcnt(1)
	v_readfirstlane_b32 s10, v3
	v_sub_u32_e32 v3, 0, v2
	v_rcp_iflag_f32_e32 v4, v4
	v_add_u32_e32 v5, s10, v1
	v_mul_f32_e32 v4, 0x4f7ffffe, v4
	v_cvt_u32_f32_e32 v4, v4
	v_mul_lo_u32 v1, v3, v4
	v_mul_hi_u32 v1, v4, v1
	v_add_u32_e32 v1, v4, v1
	v_mul_hi_u32 v1, v5, v1
	v_mul_lo_u32 v3, v1, v2
	v_sub_u32_e32 v3, v5, v3
	v_add_u32_e32 v4, 1, v1
	v_cmp_ge_u32_e32 vcc, v3, v2
	s_nop 1
	v_cndmask_b32_e32 v1, v1, v4, vcc
	v_sub_u32_e32 v4, v3, v2
	v_cndmask_b32_e32 v3, v3, v4, vcc
	v_add_u32_e32 v4, 1, v1
	v_cmp_ge_u32_e32 vcc, v3, v2
	v_add_u32_e32 v3, 1, v5
	s_nop 0
	v_cndmask_b32_e32 v1, v1, v4, vcc
	v_mul_lo_u32 v4, v2, v1
	v_add_u32_e32 v2, v4, v2
	v_cmp_ne_u32_e32 vcc, v3, v2
	s_and_saveexec_b64 s[10:11], vcc
	s_xor_b64 s[10:11], exec, s[10:11]
	s_cbranch_execz .LBB0_319
	s_waitcnt lgkmcnt(0)
	v_mov_b32_e32 v0, 0x2000
	global_load_dword v0, v0, s[8:9] offset:1024 sc1
	s_add_u32 s20, s8, 0x2400
	s_addc_u32 s21, s9, 0
	s_waitcnt vmcnt(0)
	v_cmp_eq_u32_e32 vcc, v0, v1
	s_and_saveexec_b64 s[16:17], vcc
	s_cbranch_execz .LBB0_318
	s_add_u32 s18, s50, 0x80200
	s_addc_u32 s19, s51, 0
	s_mov_b32 s34, 1
	s_mov_b64 s[22:23], 0
	v_mov_b32_e32 v0, 0
	s_branch .LBB0_309

.LBB0_318:
	s_or_b64 exec, exec, s[16:17]
	s_waitcnt vmcnt(0)
	s_waitcnt vmcnt(0)

.LBB0_336:
	s_or_b64 exec, exec, s[10:11]
	s_mov_b64 s[10:11], exec
	v_mbcnt_lo_u32_b32 v0, s10, 0
	v_mbcnt_hi_u32_b32 v0, s11, v0
	v_cmp_eq_u32_e32 vcc, 0, v0
	s_waitcnt vmcnt(0)
	s_and_saveexec_b64 s[16:17], vcc
	s_cbranch_execz .LBB0_338
	s_bcnt1_i32_b64 s10, s[10:11]
	v_mov_b32_e32 v0, 0x2000
	v_mov_b32_e32 v1, s10
	global_atomic_add v0, v1, s[8:9] offset:1024

.LBB0_569:
	s_or_b64 exec, exec, s[14:15]
	buffer_inv sc1
	v_cvt_f32_u32_e32 v4, v2
	s_waitcnt vmcnt(1)
	v_readfirstlane_b32 s10, v3
	v_sub_u32_e32 v3, 0, v2
	v_rcp_iflag_f32_e32 v4, v4
	v_add_u32_e32 v5, s10, v1
	v_mul_f32_e32 v4, 0x4f7ffffe, v4
	v_cvt_u32_f32_e32 v4, v4
	v_mul_lo_u32 v1, v3, v4
	v_mul_hi_u32 v1, v4, v1
	v_add_u32_e32 v1, v4, v1
	v_mul_hi_u32 v1, v5, v1
	v_mul_lo_u32 v3, v1, v2
	v_sub_u32_e32 v3, v5, v3
	v_add_u32_e32 v4, 1, v1
	v_cmp_ge_u32_e32 vcc, v3, v2
	s_nop 1
	v_cndmask_b32_e32 v1, v1, v4, vcc
	v_sub_u32_e32 v4, v3, v2
	v_cndmask_b32_e32 v3, v3, v4, vcc
	v_add_u32_e32 v4, 1, v1
	v_cmp_ge_u32_e32 vcc, v3, v2
	v_add_u32_e32 v3, 1, v5
	s_nop 0
	v_cndmask_b32_e32 v1, v1, v4, vcc
	v_mul_lo_u32 v4, v2, v1
	v_add_u32_e32 v2, v4, v2
	v_cmp_ne_u32_e32 vcc, v3, v2
	s_and_saveexec_b64 s[10:11], vcc
	s_xor_b64 s[10:11], exec, s[10:11]
	s_cbranch_execz .LBB0_583
	s_waitcnt lgkmcnt(0)
	v_mov_b32_e32 v0, 0x2000
	global_load_dword v0, v0, s[8:9] offset:1024 sc1
	s_add_u32 s18, s8, 0x2400
	s_addc_u32 s19, s9, 0
	s_waitcnt vmcnt(0)
	v_cmp_eq_u32_e32 vcc, v0, v1
	s_and_saveexec_b64 s[14:15], vcc
	s_cbranch_execz .LBB0_582
	s_add_u32 s16, s50, 0x80200
	s_addc_u32 s17, s51, 0
	s_mov_b32 s13, 1
	s_mov_b64 s[20:21], 0
	v_mov_b32_e32 v0, 0
	s_branch .LBB0_573

.LBB0_582:
	s_or_b64 exec, exec, s[14:15]
	s_waitcnt vmcnt(0)
	s_waitcnt vmcnt(0)

.LBB0_600:
	s_or_b64 exec, exec, s[10:11]
	s_mov_b64 s[10:11], exec
	v_mbcnt_lo_u32_b32 v0, s10, 0
	v_mbcnt_hi_u32_b32 v0, s11, v0
	v_cmp_eq_u32_e32 vcc, 0, v0
	s_waitcnt vmcnt(0)
	s_and_saveexec_b64 s[14:15], vcc
	s_cbranch_execz .LBB0_602
	s_bcnt1_i32_b64 s10, s[10:11]
	v_mov_b32_e32 v0, 0x2000
	v_mov_b32_e32 v1, s10
	global_atomic_add v0, v1, s[8:9] offset:1024

.LBB0_897:
	s_or_b64 exec, exec, s[10:11]
	buffer_inv sc1
	v_cvt_f32_u32_e32 v4, v2
	s_waitcnt vmcnt(1)
	v_readfirstlane_b32 s8, v3
	v_sub_u32_e32 v3, 0, v2
	v_rcp_iflag_f32_e32 v4, v4
	v_add_u32_e32 v5, s8, v1
	v_mul_f32_e32 v4, 0x4f7ffffe, v4
	v_cvt_u32_f32_e32 v4, v4
	v_mul_lo_u32 v1, v3, v4
	v_mul_hi_u32 v1, v4, v1
	v_add_u32_e32 v1, v4, v1
	v_mul_hi_u32 v1, v5, v1
	v_mul_lo_u32 v3, v1, v2
	v_sub_u32_e32 v3, v5, v3
	v_add_u32_e32 v4, 1, v1
	v_cmp_ge_u32_e32 vcc, v3, v2
	s_nop 1
	v_cndmask_b32_e32 v1, v1, v4, vcc
	v_sub_u32_e32 v4, v3, v2
	v_cndmask_b32_e32 v3, v3, v4, vcc
	v_add_u32_e32 v4, 1, v1
	v_cmp_ge_u32_e32 vcc, v3, v2
	v_add_u32_e32 v3, 1, v5
	s_nop 0
	v_cndmask_b32_e32 v1, v1, v4, vcc
	v_mul_lo_u32 v4, v2, v1
	v_add_u32_e32 v2, v4, v2
	v_cmp_ne_u32_e32 vcc, v3, v2
	s_and_saveexec_b64 s[8:9], vcc
	s_xor_b64 s[8:9], exec, s[8:9]
	s_cbranch_execz .LBB0_911
	s_waitcnt lgkmcnt(0)
	v_mov_b32_e32 v0, 0x2000
	global_load_dword v0, v0, s[6:7] offset:1024 sc1
	s_add_u32 s14, s6, 0x2400
	s_addc_u32 s15, s7, 0
	s_waitcnt vmcnt(0)
	v_cmp_eq_u32_e32 vcc, v0, v1
	s_and_saveexec_b64 s[10:11], vcc
	s_cbranch_execz .LBB0_910
	s_add_u32 s12, s50, 0x80200
	s_addc_u32 s13, s51, 0
	s_mov_b32 s26, 1
	s_mov_b64 s[16:17], 0
	v_mov_b32_e32 v0, 0
	s_branch .LBB0_901

.LBB0_910:
	s_or_b64 exec, exec, s[10:11]
	s_waitcnt vmcnt(0)
	s_waitcnt vmcnt(0)

.LBB0_928:
	s_or_b64 exec, exec, s[8:9]
	s_mov_b64 s[8:9], exec
	v_mbcnt_lo_u32_b32 v0, s8, 0
	v_mbcnt_hi_u32_b32 v0, s9, v0
	v_cmp_eq_u32_e32 vcc, 0, v0
	s_waitcnt vmcnt(0)
	s_and_saveexec_b64 s[10:11], vcc
	s_cbranch_execz .LBB0_930
	s_bcnt1_i32_b64 s8, s[8:9]
	v_mov_b32_e32 v0, 0x2000
	v_mov_b32_e32 v1, s8
	global_atomic_add v0, v1, s[6:7] offset:1024

.LBB0_1024:
	s_or_b64 exec, exec, s[16:17]
	buffer_inv sc1
	v_cvt_f32_u32_e32 v4, v2
	s_waitcnt vmcnt(1)
	v_readfirstlane_b32 s14, v3
	v_sub_u32_e32 v3, 0, v2
	v_rcp_iflag_f32_e32 v4, v4
	v_add_u32_e32 v5, s14, v1
	v_mul_f32_e32 v4, 0x4f7ffffe, v4
	v_cvt_u32_f32_e32 v4, v4
	v_mul_lo_u32 v1, v3, v4
	v_mul_hi_u32 v1, v4, v1
	v_add_u32_e32 v1, v4, v1
	v_mul_hi_u32 v1, v5, v1
	v_mul_lo_u32 v3, v1, v2
	v_sub_u32_e32 v3, v5, v3
	v_add_u32_e32 v4, 1, v1
	v_cmp_ge_u32_e32 vcc, v3, v2
	s_nop 1
	v_cndmask_b32_e32 v1, v1, v4, vcc
	v_sub_u32_e32 v4, v3, v2
	v_cndmask_b32_e32 v3, v3, v4, vcc
	v_add_u32_e32 v4, 1, v1
	v_cmp_ge_u32_e32 vcc, v3, v2
	v_add_u32_e32 v3, 1, v5
	s_nop 0
	v_cndmask_b32_e32 v1, v1, v4, vcc
	v_mul_lo_u32 v4, v2, v1
	v_add_u32_e32 v2, v4, v2
	v_cmp_ne_u32_e32 vcc, v3, v2
	s_and_saveexec_b64 s[14:15], vcc
	s_xor_b64 s[14:15], exec, s[14:15]
	s_cbranch_execz .LBB0_1038
	s_waitcnt lgkmcnt(0)
	v_mov_b32_e32 v0, 0x2000
	global_load_dword v0, v0, s[8:9] offset:1024 sc1
	s_add_u32 s20, s8, 0x2400
	s_addc_u32 s21, s9, 0
	s_waitcnt vmcnt(0)
	v_cmp_eq_u32_e32 vcc, v0, v1
	s_and_saveexec_b64 s[16:17], vcc
	s_cbranch_execz .LBB0_1037
	s_add_u32 s18, s50, 0x80200
	s_addc_u32 s19, s51, 0
	s_mov_b32 s34, 1
	s_mov_b64 s[22:23], 0
	v_mov_b32_e32 v0, 0
	s_branch .LBB0_1028

.LBB0_1055:
	s_or_b64 exec, exec, s[14:15]
	s_mov_b64 s[14:15], exec
	v_mbcnt_lo_u32_b32 v0, s14, 0
	v_mbcnt_hi_u32_b32 v0, s15, v0
	v_cmp_eq_u32_e32 vcc, 0, v0
	s_waitcnt vmcnt(0)
	s_and_saveexec_b64 s[16:17], vcc
	s_cbranch_execz .LBB0_1057
	s_bcnt1_i32_b64 s14, s[14:15]
	v_mov_b32_e32 v0, 0x2000
	v_mov_b32_e32 v1, s14
	global_atomic_add v0, v1, s[8:9] offset:1024

.LBB0_1202:
	s_or_b64 exec, exec, s[12:13]
	buffer_inv sc1
	v_cvt_f32_u32_e32 v4, v2
	s_waitcnt vmcnt(1)
	v_readfirstlane_b32 s10, v3
	v_sub_u32_e32 v3, 0, v2
	v_rcp_iflag_f32_e32 v4, v4
	v_add_u32_e32 v5, s10, v1
	v_mul_f32_e32 v4, 0x4f7ffffe, v4
	v_cvt_u32_f32_e32 v4, v4
	v_mul_lo_u32 v1, v3, v4
	v_mul_hi_u32 v1, v4, v1
	v_add_u32_e32 v1, v4, v1
	v_mul_hi_u32 v1, v5, v1
	v_mul_lo_u32 v3, v1, v2
	v_sub_u32_e32 v3, v5, v3
	v_add_u32_e32 v4, 1, v1
	v_cmp_ge_u32_e32 vcc, v3, v2
	s_nop 1
	v_cndmask_b32_e32 v1, v1, v4, vcc
	v_sub_u32_e32 v4, v3, v2
	v_cndmask_b32_e32 v3, v3, v4, vcc
	v_add_u32_e32 v4, 1, v1
	v_cmp_ge_u32_e32 vcc, v3, v2
	v_add_u32_e32 v3, 1, v5
	s_nop 0
	v_cndmask_b32_e32 v1, v1, v4, vcc
	v_mul_lo_u32 v4, v2, v1
	v_add_u32_e32 v2, v4, v2
	v_cmp_ne_u32_e32 vcc, v3, v2
	s_and_saveexec_b64 s[10:11], vcc
	s_xor_b64 s[10:11], exec, s[10:11]
	s_cbranch_execz .LBB0_1216
	s_waitcnt lgkmcnt(0)
	v_mov_b32_e32 v0, 0x2000
	global_load_dword v0, v0, s[8:9] offset:1024 sc1
	s_add_u32 s16, s8, 0x2400
	s_addc_u32 s17, s9, 0
	s_waitcnt vmcnt(0)
	v_cmp_eq_u32_e32 vcc, v0, v1
	s_and_saveexec_b64 s[12:13], vcc
	s_cbranch_execz .LBB0_1215
	s_add_u32 s14, s50, 0x80200
	s_addc_u32 s15, s51, 0
	s_mov_b32 s28, 1
	s_mov_b64 s[18:19], 0
	v_mov_b32_e32 v0, 0
	s_branch .LBB0_1206

.LBB0_1215:
	s_or_b64 exec, exec, s[12:13]
	s_waitcnt vmcnt(0)
	s_waitcnt vmcnt(0)

.LBB0_1233:
	s_or_b64 exec, exec, s[10:11]
	s_mov_b64 s[10:11], exec
	v_mbcnt_lo_u32_b32 v0, s10, 0
	v_mbcnt_hi_u32_b32 v0, s11, v0
	v_cmp_eq_u32_e32 vcc, 0, v0
	s_waitcnt vmcnt(0)
	s_and_saveexec_b64 s[12:13], vcc
	s_cbranch_execz .LBB0_1235
	s_bcnt1_i32_b64 s10, s[10:11]
	v_mov_b32_e32 v0, 0x2000
	v_mov_b32_e32 v1, s10
	global_atomic_add v0, v1, s[8:9] offset:1024

.LBB0_1306:
	s_or_b64 exec, exec, s[14:15]
	buffer_inv sc1
	v_cvt_f32_u32_e32 v4, v2
	s_waitcnt vmcnt(1)
	v_readfirstlane_b32 s10, v3
	v_sub_u32_e32 v3, 0, v2
	v_rcp_iflag_f32_e32 v4, v4
	v_add_u32_e32 v5, s10, v1
	v_mul_f32_e32 v4, 0x4f7ffffe, v4
	v_cvt_u32_f32_e32 v4, v4
	v_mul_lo_u32 v1, v3, v4
	v_mul_hi_u32 v1, v4, v1
	v_add_u32_e32 v1, v4, v1
	v_mul_hi_u32 v1, v5, v1
	v_mul_lo_u32 v3, v1, v2
	v_sub_u32_e32 v3, v5, v3
	v_add_u32_e32 v4, 1, v1
	v_cmp_ge_u32_e32 vcc, v3, v2
	s_nop 1
	v_cndmask_b32_e32 v1, v1, v4, vcc
	v_sub_u32_e32 v4, v3, v2
	v_cndmask_b32_e32 v3, v3, v4, vcc
	v_add_u32_e32 v4, 1, v1
	v_cmp_ge_u32_e32 vcc, v3, v2
	v_add_u32_e32 v3, 1, v5
	s_nop 0
	v_cndmask_b32_e32 v1, v1, v4, vcc
	v_mul_lo_u32 v4, v2, v1
	v_add_u32_e32 v2, v4, v2
	v_cmp_ne_u32_e32 vcc, v3, v2
	s_and_saveexec_b64 s[10:11], vcc
	s_xor_b64 s[10:11], exec, s[10:11]
	s_cbranch_execz .LBB0_1320
	s_waitcnt lgkmcnt(0)
	v_mov_b32_e32 v0, 0x2000
	global_load_dword v0, v0, s[8:9] offset:1024 sc1
	s_add_u32 s18, s8, 0x2400
	s_addc_u32 s19, s9, 0
	s_waitcnt vmcnt(0)
	v_cmp_eq_u32_e32 vcc, v0, v1
	s_and_saveexec_b64 s[14:15], vcc
	s_cbranch_execz .LBB0_1319
	s_add_u32 s16, s50, 0x80200
	s_addc_u32 s17, s51, 0
	s_mov_b32 s30, 1
	s_mov_b64 s[20:21], 0
	v_mov_b32_e32 v0, 0
	s_branch .LBB0_1310
